# ssd_out latch wait tightened to vmcnt(10): also guarantees the four prefetched dt values read by the next unit's scan (was vmcnt(14), formally too loose on the short prefetch path)
# baseline (speedup 1.0000x reference)
.LBB0_439:
	s_lshl_b32 s68, s86, 7
	s_add_u32 s82, s88, s68
	v_add_u32_e32 v136, s90, v169
	v_mov_b32_e32 v137, v145
	s_addc_u32 s83, s89, 0
	v_lshlrev_b64 v[136:137], 10, v[136:137]
	v_lshl_add_u64 v[136:137], s[82:83], 0, v[136:137]
	v_pk_add_f32 v[114:115], v[122:123], v[114:115]
	v_pk_add_f32 v[112:113], v[120:121], v[112:113]
	v_lshl_add_u64 v[136:137], v[150:151], 1, v[136:137]
	v_cvt_pk_bf16_f32 v112, v112, v113
	v_cvt_pk_bf16_f32 v113, v114, v115
	global_store_dwordx2 v[136:137], v[112:113], off
	v_pk_add_f32 v[112:113], v[126:127], v[118:119]
	v_pk_add_f32 v[114:115], v[124:125], v[116:117]
	v_pk_add_f32 v[110:111], v[130:131], v[110:111]
	v_pk_add_f32 v[108:109], v[128:129], v[108:109]
	v_pk_add_f32 v[106:107], v[134:135], v[106:107]
	v_pk_add_f32 v[104:105], v[132:133], v[104:105]
	v_cvt_pk_bf16_f32 v114, v114, v115
	v_cvt_pk_bf16_f32 v115, v112, v113
	v_cvt_pk_bf16_f32 v108, v108, v109
	v_cvt_pk_bf16_f32 v109, v110, v111
	v_cvt_pk_bf16_f32 v104, v104, v105
	v_cvt_pk_bf16_f32 v105, v106, v107
	s_xor_b32 s70, s70, 1
	s_add_i32 s85, s85, 1
	s_andn2_b64 vcc, exec, s[80:81]
	s_mov_b32 s90, s87
	s_mov_b32 s86, s71
	global_store_dwordx2 v[136:137], v[114:115], off offset:32
	global_store_dwordx2 v[136:137], v[108:109], off offset:64
	global_store_dwordx2 v[136:137], v[104:105], off offset:96
	s_waitcnt vmcnt(10)
	v_mul_f32_e32 v170, 0x3fb8aa3b, v170
	v_mul_f32_e32 v171, 0x3fb8aa3b, v171
	v_exp_f32_e32 v170, v170
	v_exp_f32_e32 v171, v171
	s_nop 0
	v_xor_b32_e32 v178, 0x80000000, v170
	v_xor_b32_e32 v182, 0x80000000, v171
	s_cbranch_vccz .LBB0_595
